# static s_setprio 1 for waves 4-7 at GEMM phase start (no per-block flips)
# baseline (speedup 1.0000x reference)
; #define PG8_BAR __builtin_amdgcn_s_barrier()
;     __host__ __device__ bool next(int i, Unit& u) const {
;         const long L = (long)i * G + c; if (L >= nwg) return false;
;         int wgid = (int)L; { const int q = nwg / NXCD, r = nwg % NXCD, xcd = wgid % NXCD, off = wgid / NXCD; wgid = (xcd < r ? xcd * (q + 1) : r * (q + 1) + (xcd - r) * q) + off; }
;         int nig = WGM * nN, nr = nNr;
;     ...
;         asm volatile("" : "+s"(nig), "+s"(nr));
;     ...
;         const int gid = wgid / nig, fm = gid * WGM, gsz = (nM - fm) < WGM ? (nM - fm) : WGM;
; template <class Epi, class Sched, bool ALIGN_EPI = true>
; __device__ __forceinline__ void gemm_phase(PG8_LAS unsigned char* lds, const Gemm g, const Sched& S, const Epi& E, const int tid) {
;     const int wid = __builtin_amdgcn_readfirstlane(tid >> 6), lane = tid & 63, wr = wid >> 2, wc = wid & 3, fr = lane & 15, fq = lane >> 4;
;     unsigned voffA[2], voffB[2];
; #pragma unroll
;     for (int i = 0; i < 2; ++i) { int R, C; stage_rc(tid * 16 + i * 8192, R, C); const int Rb = Epi::PERM ? ((R & ~31) + perm32(R & 31)) : R;
;         voffA[i] = (unsigned)(R * g.lda + C) * 2u; voffB[i] = (unsigned)(Rb * g.ldb + C) * 2u; }
;     const size_t kstep = (size_t)(BK * 2);
;     const size_t hstepA = (size_t)HALF * g.lda * 2, hstepB = (size_t)HALF * g.ldb * 2;
;     const size_t tstepA = 2 * hstepA, tstepB = 2 * hstepB;
;     const unsigned ldsw = (unsigned)wid * 1024u;
;     const int aoff = lds_byte(wr * 64 + fr, fq * 8), boff = lds_byte(wc * 32 + fr, fq * 8);
;     ...
;     Unit cur, nxt; int ui = 0;
;     if (!S.next(0, cur)) return;
;     f32x4 acc[2][2][4][2];
; #pragma unroll
;     for (int a = 0; a < 2; ++a)
; #pragma unroll
;         for (int b = 0; b < 2; ++b)
; #pragma unroll
;             for (int m = 0; m < 4; ++m)
; #pragma unroll
;                 for (int n = 0; n < 2; ++n) acc[a][b][m][n] = (f32x4){0.f, 0.f, 0.f, 0.f};
;     bf16x8 At[4][2], B0[2][2], B1[2][2];
;     const char* cA = (const char*)g.A + (size_t)cur.pm * tstepA + (size_t)cur.grp * g.gsA + (size_t)cur.kt0 * kstep; const char* cB = (const char*)g.Bt + (size_t)cur.pn * tstepB + (size_t)cur.grp * g.gsB + (size_t)cur.kt0 * kstep;
;     S.a_ready(cur);
;     PG8_STAGE(PG8_SB(0, 0), cB, voffB); PG8_STAGE(PG8_SB(0, 1), cB + hstepB, voffB); PG8_STAGE(PG8_SA(0, 0), cA, voffA); PG8_STAGE(PG8_SA(0, 1), cA + hstepA, voffA);
;     if (wr == 1) PG8_BAR;
.LBB0_417:
	v_readlane_b32 s0, v255, 24
	s_lshr_b32 s30, s0, 5
	v_mov_b32_e32 v17, v247
	s_cmp_ge_i32 s2, s30
	s_mov_b64 s[0:1], s[82:83]
	v_readfirstlane_b32 s8, v17
	s_cbranch_scc1 .LBB0_445
	v_lshlrev_b32_e32 v2, 4, v17
	v_add_u32_e32 v4, 0x2000, v2
	v_ashrrev_i32_e32 v5, 31, v4
	v_lshrrev_b32_e32 v5, 22, v5
	v_add_u32_e32 v5, v4, v5
	v_ashrrev_i32_e32 v12, 10, v5
	v_mul_i32_i24_e32 v5, 0x400, v12
	s_waitcnt lgkmcnt(0)
	s_load_dwordx2 s[38:39], s[0:1], 0xb0
	s_load_dwordx2 s[12:13], s[0:1], 0x78
	v_sub_u32_e32 v4, v4, v5
	v_lshrrev_b32_e32 v5, 4, v4
	s_mov_b32 s87, s31
	v_readlane_b32 s0, v255, 24
	v_bitop3_b32 v4, v5, v4, 32 bitop3:0x6c
	s_lshr_b32 s18, s0, 8
	s_lshl_b64 s[0:1], s[86:87], 21
	v_ashrrev_i32_e32 v5, 31, v4
	s_waitcnt lgkmcnt(0)
	s_add_u32 s19, s38, 0x21e00000
	v_lshrrev_b32_e32 v5, 26, v5
	s_addc_u32 s64, s39, 0
	v_add_u32_e32 v5, v4, v5
	v_lshlrev_b32_e32 v6, 3, v12
	s_add_u32 s0, s38, s0
	v_ashrrev_i32_e32 v13, 6, v5
	v_and_b32_e32 v6, -16, v6
	s_addc_u32 s1, s39, s1
	v_add_u32_e32 v6, v13, v6
	s_add_u32 s65, s0, 0x4400000
	v_and_b32_e32 v7, 3, v13
	s_mov_b32 s0, 0x3fffe0
	v_lshrrev_b32_e32 v8, 2, v6
	v_lshlrev_b32_e32 v9, 1, v6
	v_and_or_b32 v7, v6, s0, v7
	v_and_b32_e32 v8, 4, v8
	v_and_b32_e32 v9, 24, v9
	v_and_b32_e32 v5, 0xc0, v5
	v_or3_b32 v7, v7, v8, v9
	v_sub_u32_e32 v4, v4, v5
	v_mov_b32_e32 v9, 1
	v_lshlrev_b32_e32 v8, 5, v12
	v_ashrrev_i16_sdwa v4, v9, sext(v4) dst_sel:DWORD dst_unused:UNUSED_PAD src0_sel:DWORD src1_sel:BYTE_0
	v_and_b32_e32 v8, 32, v8
	v_bfe_i32 v14, v4, 0, 16
	v_add_lshl_u32 v4, v8, v14, 1
	v_lshl_add_u32 v210, v7, 10, v4
	v_lshl_add_u32 v212, v6, 12, v4
	v_bfe_i32 v4, v17, 27, 1
	v_lshrrev_b32_e32 v4, 22, v4
	v_add_u32_e32 v4, v2, v4
	v_and_b32_e32 v4, 0xfffffc00, v4
	v_sub_u32_e32 v2, v2, v4
	v_lshrrev_b32_e32 v4, 4, v2
	v_ashrrev_i32_e32 v5, 31, v17
	v_bitop3_b32 v2, v4, v2, 32 bitop3:0x6c
	v_lshrrev_b32_e32 v5, 26, v5
	v_ashrrev_i32_e32 v4, 31, v2
	v_add_u32_e32 v5, v17, v5
	v_lshrrev_b32_e32 v4, 26, v4
	v_ashrrev_i32_e32 v16, 6, v5
	v_add_u32_e32 v4, v2, v4
	v_lshlrev_b32_e32 v5, 3, v16
	v_ashrrev_i32_e32 v15, 6, v4
	v_and_b32_e32 v5, -16, v5
	v_add_u32_e32 v5, v15, v5
	v_and_b32_e32 v6, 3, v15
	s_addc_u32 s66, s1, 0
	v_and_or_b32 v6, v5, s0, v6
	s_mov_b32 s1, 2
	s_mov_b32 s0, 32
	v_and_b32_e32 v4, 0xc0, v4
	s_abs_i32 s4, s0
	v_sub_u32_e32 v2, v2, v4
	v_cvt_f32_u32_e32 v4, s4
	v_ashrrev_i16_sdwa v2, v9, sext(v2) dst_sel:DWORD dst_unused:UNUSED_PAD src0_sel:DWORD src1_sel:BYTE_0
	v_bfe_i32 v18, v2, 0, 16
	v_readlane_b32 s5, v254, 44
	v_rcp_iflag_f32_e32 v2, v4
	s_or_b32 s5, s18, s5
	v_readlane_b32 s6, v254, 47
	s_sub_i32 s10, 0, s4
	v_mul_f32_e32 v2, 0x4f7ffffe, v2
	v_cvt_u32_f32_e32 v2, v2
	s_mul_i32 s5, s5, s6
	v_readlane_b32 s6, v254, 48
	s_add_i32 s5, s5, s6
	v_readfirstlane_b32 s11, v2
	s_mul_i32 s10, s10, s11
	s_mul_hi_u32 s10, s11, s10
	s_abs_i32 s7, s5
	s_add_i32 s11, s11, s10
	s_mul_hi_u32 s10, s7, s11
	s_mul_i32 s11, s10, s4
	s_ashr_i32 s9, s8, 6
	s_xor_b32 s6, s5, s0
	s_sub_i32 s7, s7, s11
	s_ashr_i32 s20, s8, 8
	s_lshl_b32 s67, s9, 10
	s_ashr_i32 s6, s6, 31
	s_add_i32 s11, s10, 1
	s_sub_i32 s15, s7, s4
	s_cmp_ge_u32 s7, s4
	s_cselect_b32 s10, s11, s10
	s_cselect_b32 s7, s15, s7
	s_add_i32 s11, s10, 1
	s_cmp_ge_u32 s7, s4
	s_cselect_b32 s4, s11, s10
	s_xor_b32 s4, s4, s6
	s_sub_i32 s4, s4, s6
	s_lshl_b32 s6, s4, 2
	s_sub_i32 s7, s18, s6
	s_min_i32 s7, s7, 4
	s_abs_i32 s10, s7
	v_cvt_f32_u32_e32 v4, s10
	s_sub_i32 s11, 0, s10
	s_mul_i32 s4, s4, s0
	s_sub_i32 s0, s5, s4
	v_rcp_iflag_f32_e32 v4, v4
	s_abs_i32 s5, s0
	s_xor_b32 s4, s0, s7
	s_ashr_i32 s4, s4, 31
	v_mul_f32_e32 v4, 0x4f7ffffe, v4
	v_cvt_u32_f32_e32 v4, v4
	v_lshrrev_b32_e32 v7, 2, v5
	v_lshlrev_b32_e32 v8, 1, v5
	v_and_b32_e32 v7, 4, v7
	v_readfirstlane_b32 s15, v4
	s_mul_i32 s11, s11, s15
	s_mul_hi_u32 s11, s15, s11
	s_add_i32 s15, s15, s11
	s_mul_hi_u32 s11, s5, s15
	s_mul_i32 s15, s11, s10
	s_sub_i32 s5, s5, s15
	s_add_i32 s15, s11, 1
	s_sub_i32 s16, s5, s10
	s_cmp_ge_u32 s5, s10
	s_cselect_b32 s11, s15, s11
	s_cselect_b32 s5, s16, s5
	s_add_i32 s15, s11, 1
	s_cmp_ge_u32 s5, s10
	s_cselect_b32 s5, s15, s11
	s_abs_i32 s10, s1
	v_cvt_f32_u32_e32 v4, s10
	s_xor_b32 s5, s5, s4
	s_sub_i32 s5, s5, s4
	s_mul_i32 s4, s5, s7
	v_rcp_iflag_f32_e32 v4, v4
	s_sub_i32 s7, 0, s10
	s_sub_i32 s0, s0, s4
	s_add_i32 s0, s0, s6
	v_mul_f32_e32 v4, 0x4f7ffffe, v4
	v_cvt_u32_f32_e32 v4, v4
	s_abs_i32 s6, s5
	s_xor_b32 s4, s5, s1
	s_ashr_i32 s4, s4, 31
	v_readfirstlane_b32 s11, v4
	s_mul_i32 s7, s7, s11
	s_mul_hi_u32 s7, s11, s7
	s_add_i32 s11, s11, s7
	s_mul_hi_u32 s7, s6, s11
	s_mul_i32 s11, s7, s10
	s_sub_i32 s6, s6, s11
	s_add_i32 s11, s7, 1
	s_sub_i32 s15, s6, s10
	s_cmp_ge_u32 s6, s10
	s_cselect_b32 s7, s11, s7
	s_cselect_b32 s6, s15, s6
	s_add_i32 s11, s7, 1
	s_cmp_ge_u32 s6, s10
	s_cselect_b32 s6, s11, s7
	s_xor_b32 s6, s6, s4
	s_sub_i32 s4, s6, s4
	s_mul_i32 s1, s4, s1
	s_sub_i32 s10, s5, s1
	s_ashr_i32 s1, s0, 31
	s_ashr_i32 s5, s4, 31
	s_ashr_i32 s11, s10, 31
	s_lshl_b64 s[6:7], s[0:1], 20
	s_lshl_b64 s[42:43], s[4:5], 10
	s_lshl_b64 s[22:23], s[10:11], 18
	v_and_b32_e32 v8, 24, v8
	s_add_u32 s1, s65, s22
	v_or3_b32 v6, v6, v7, v8
	v_lshlrev_b32_e32 v7, 5, v16
	s_addc_u32 s11, s66, s23
	s_lshl_b64 s[22:23], s[4:5], 19
	v_and_b32_e32 v7, 32, v7
	s_add_u32 s22, s1, s22
	v_add_lshl_u32 v7, v7, v18, 1
	s_addc_u32 s23, s11, s23
	s_add_i32 s11, s67, 0
	v_lshl_add_u32 v2, v6, 10, v7
	s_add_i32 m0, s11, 0x10000
	v_lshl_add_u32 v214, v5, 12, v7
	global_load_lds_dwordx4 v2, s[22:23]
	s_add_i32 m0, s11, 0x12000
	s_add_u32 s1, s19, s6
	s_addc_u32 s5, s64, s7
	s_add_u32 s6, s22, 0x20000
	global_load_lds_dwordx4 v210, s[22:23]
	s_addc_u32 s7, s23, 0
	s_add_i32 m0, s11, 0x14000
	v_mov_b32_e32 v211, v3
	global_load_lds_dwordx4 v2, s[6:7]
	s_add_i32 m0, s11, 0x16000
	s_add_u32 s62, s1, s42
	s_addc_u32 s63, s5, s43
	s_add_i32 s68, s11, 0x2000
	global_load_lds_dwordx4 v210, s[6:7]
	s_mov_b32 m0, s11
	s_add_u32 s6, s62, 0x80000
	global_load_lds_dwordx4 v214, s[62:63]
	s_mov_b32 m0, s68
	s_addc_u32 s7, s63, 0
	s_add_i32 s69, s11, 0x4000
	global_load_lds_dwordx4 v212, s[62:63]
	s_mov_b32 m0, s69
	s_add_i32 s70, s11, 0x6000
	global_load_lds_dwordx4 v214, s[6:7]
	s_mov_b32 m0, s70
	v_mov_b32_e32 v215, v3
	global_load_lds_dwordx4 v212, s[6:7]
	v_mov_b32_e32 v213, v3
	s_cmp_eq_u32 s20, 1
	v_lshl_add_u64 v[10:11], s[22:23], 0, v[2:3]
	v_lshl_add_u64 v[8:9], s[22:23], 0, v[210:211]
	v_lshl_add_u64 v[4:5], s[62:63], 0, v[214:215]
	s_cselect_b64 s[6:7], -1, 0
	s_cmp_lg_u32 s20, 1
	v_lshl_add_u64 v[6:7], s[62:63], 0, v[212:213]
	s_cbranch_scc1 .LBB0_420
	s_setprio 1
	s_barrier

; #define PG8_BAR __builtin_amdgcn_s_barrier()
;     __host__ __device__ bool next(int i, Unit& u) const {
;         const long L = (long)i * G + c; if (L >= nwg) return false;
;         int wgid = (int)L; { const int q = nwg / NXCD, r = nwg % NXCD, xcd = wgid % NXCD, off = wgid / NXCD; wgid = (xcd < r ? xcd * (q + 1) : r * (q + 1) + (xcd - r) * q) + off; }
;         int nig = WGM * nN, nr = nNr;
;     ...
;         asm volatile("" : "+s"(nig), "+s"(nr));
;     ...
;         const int gid = wgid / nig, fm = gid * WGM, gsz = (nM - fm) < WGM ? (nM - fm) : WGM;
; template <class Epi, class Sched, bool ALIGN_EPI = true>
; __device__ __forceinline__ void gemm_phase(PG8_LAS unsigned char* lds, const Gemm g, const Sched& S, const Epi& E, const int tid) {
;     const int wid = __builtin_amdgcn_readfirstlane(tid >> 6), lane = tid & 63, wr = wid >> 2, wc = wid & 3, fr = lane & 15, fq = lane >> 4;
;     unsigned voffA[2], voffB[2];
; #pragma unroll
;     for (int i = 0; i < 2; ++i) { int R, C; stage_rc(tid * 16 + i * 8192, R, C); const int Rb = Epi::PERM ? ((R & ~31) + perm32(R & 31)) : R;
;         voffA[i] = (unsigned)(R * g.lda + C) * 2u; voffB[i] = (unsigned)(Rb * g.ldb + C) * 2u; }
;     const size_t kstep = (size_t)(BK * 2);
;     const size_t hstepA = (size_t)HALF * g.lda * 2, hstepB = (size_t)HALF * g.ldb * 2;
;     const size_t tstepA = 2 * hstepA, tstepB = 2 * hstepB;
;     const unsigned ldsw = (unsigned)wid * 1024u;
;     const int aoff = lds_byte(wr * 64 + fr, fq * 8), boff = lds_byte(wc * 32 + fr, fq * 8);
;     ...
;     Unit cur, nxt; int ui = 0;
;     if (!S.next(0, cur)) return;
;     f32x4 acc[2][2][4][2];
; #pragma unroll
;     for (int a = 0; a < 2; ++a)
; #pragma unroll
;         for (int b = 0; b < 2; ++b)
; #pragma unroll
;             for (int m = 0; m < 4; ++m)
; #pragma unroll
;                 for (int n = 0; n < 2; ++n) acc[a][b][m][n] = (f32x4){0.f, 0.f, 0.f, 0.f};
;     bf16x8 At[4][2], B0[2][2], B1[2][2];
;     const char* cA = (const char*)g.A + (size_t)cur.pm * tstepA + (size_t)cur.grp * g.gsA + (size_t)cur.kt0 * kstep; const char* cB = (const char*)g.Bt + (size_t)cur.pn * tstepB + (size_t)cur.grp * g.gsB + (size_t)cur.kt0 * kstep;
;     S.a_ready(cur);
;     PG8_STAGE(PG8_SB(0, 0), cB, voffB); PG8_STAGE(PG8_SB(0, 1), cB + hstepB, voffB); PG8_STAGE(PG8_SA(0, 0), cA, voffA); PG8_STAGE(PG8_SA(0, 1), cA + hstepA, voffA);
;     if (wr == 1) PG8_BAR;
.LBB0_503:
	v_readlane_b32 s4, v254, 22
	v_mov_b32_e32 v17, v247
	v_readlane_b32 s5, v254, 23
	s_mov_b64 s[0:1], s[82:83]
	v_readfirstlane_b32 s8, v17
	s_andn2_b64 vcc, exec, s[4:5]
	s_cbranch_vccnz .LBB0_519
	v_lshlrev_b32_e32 v2, 4, v17
	v_add_u32_e32 v4, 0x2000, v2
	v_ashrrev_i32_e32 v5, 31, v4
	v_lshrrev_b32_e32 v5, 22, v5
	v_add_u32_e32 v5, v4, v5
	v_ashrrev_i32_e32 v12, 10, v5
	v_mul_i32_i24_e32 v5, 0x400, v12
	v_sub_u32_e32 v4, v4, v5
	v_lshrrev_b32_e32 v5, 4, v4
	v_bitop3_b32 v4, v5, v4, 32 bitop3:0x6c
	v_ashrrev_i32_e32 v5, 31, v4
	v_lshrrev_b32_e32 v5, 26, v5
	v_add_u32_e32 v5, v4, v5
	v_lshlrev_b32_e32 v6, 3, v12
	v_ashrrev_i32_e32 v13, 6, v5
	v_and_b32_e32 v6, -16, v6
	v_add_u32_e32 v6, v13, v6
	v_and_b32_e32 v7, 3, v13
	s_mov_b32 s3, 0xfffe0
	v_lshrrev_b32_e32 v8, 2, v6
	v_lshlrev_b32_e32 v9, 1, v6
	v_and_b32_e32 v5, 0xc0, v5
	v_and_or_b32 v7, v6, s3, v7
	v_and_b32_e32 v8, 4, v8
	v_and_b32_e32 v9, 24, v9
	v_sub_u32_e32 v4, v4, v5
	v_mov_b32_e32 v10, 1
	v_or3_b32 v7, v7, v8, v9
	v_lshlrev_b32_e32 v8, 5, v12
	v_ashrrev_i16_sdwa v4, v10, sext(v4) dst_sel:DWORD dst_unused:UNUSED_PAD src0_sel:DWORD src1_sel:BYTE_0
	v_and_b32_e32 v8, 32, v8
	v_bfe_i32 v14, v4, 0, 16
	s_load_dwordx2 s[0:1], s[0:1], 0xb0
	v_add_lshl_u32 v4, v8, v14, 1
	v_lshl_add_u32 v132, v7, 12, v4
	v_lshl_add_u32 v134, v6, 12, v4
	v_bfe_i32 v4, v17, 27, 1
	v_lshrrev_b32_e32 v4, 22, v4
	v_add_u32_e32 v4, v2, v4
	v_and_b32_e32 v4, 0xfffffc00, v4
	s_mul_i32 s30, s86, 0xc80000
	s_waitcnt lgkmcnt(0)
	s_add_u32 s9, s0, 0x1da00000
	v_sub_u32_e32 v2, v2, v4
	s_addc_u32 s18, s1, 0
	s_lshl_b64 s[4:5], s[30:31], 1
	v_lshrrev_b32_e32 v4, 4, v2
	v_ashrrev_i32_e32 v5, 31, v17
	s_add_u32 s4, s0, s4
	v_bitop3_b32 v2, v4, v2, 32 bitop3:0x6c
	v_lshrrev_b32_e32 v5, 26, v5
	s_addc_u32 s5, s1, s5
	v_ashrrev_i32_e32 v4, 31, v2
	v_add_u32_e32 v5, v17, v5
	s_add_u32 s19, s4, 0x200000
	v_lshrrev_b32_e32 v4, 26, v4
	v_ashrrev_i32_e32 v16, 6, v5
	s_movk_i32 s6, 0x64
	s_mov_b32 s7, 25
	s_addc_u32 s20, s5, 0
	v_add_u32_e32 v4, v2, v4
	v_lshlrev_b32_e32 v5, 3, v16
	s_abs_i32 s10, s6
	v_ashrrev_i32_e32 v15, 6, v4
	v_and_b32_e32 v5, -16, v5
	v_cvt_f32_u32_e32 v9, s10
	v_add_u32_e32 v5, v15, v5
	v_and_b32_e32 v6, 3, v15
	v_lshrrev_b32_e32 v7, 2, v5
	v_lshlrev_b32_e32 v8, 1, v5
	v_and_or_b32 v6, v5, s3, v6
	v_and_b32_e32 v7, 4, v7
	v_and_b32_e32 v8, 24, v8
	v_or3_b32 v6, v6, v7, v8
	v_rcp_iflag_f32_e32 v8, v9
	v_and_b32_e32 v4, 0xc0, v4
	v_sub_u32_e32 v2, v2, v4
	s_ashr_i32 s11, s6, 31
	v_mul_f32_e32 v4, 0x4f7ffffe, v8
	v_cvt_u32_f32_e32 v4, v4
	v_readlane_b32 s12, v254, 52
	s_xor_b32 s11, s12, s11
	s_sub_i32 s12, 0, s10
	v_readfirstlane_b32 s13, v4
	s_mul_i32 s12, s12, s13
	s_mul_hi_u32 s12, s13, s12
	s_add_i32 s13, s13, s12
	v_readlane_b32 s15, v254, 54
	s_mul_hi_u32 s12, s15, s13
	s_mul_i32 s13, s12, s10
	s_ashr_i32 s4, s8, 6
	s_sub_i32 s13, s15, s13
	s_ashr_i32 s5, s8, 8
	s_lshl_b32 s21, s4, 10
	s_add_i32 s22, s12, 1
	s_sub_i32 s23, s13, s10
	s_cmp_ge_u32 s13, s10
	s_cselect_b32 s12, s22, s12
	s_cselect_b32 s13, s23, s13
	s_add_i32 s22, s12, 1
	s_cmp_ge_u32 s13, s10
	s_cselect_b32 s10, s22, s12
	s_xor_b32 s10, s10, s11
	s_sub_i32 s10, s10, s11
	s_lshl_b32 s11, s10, 2
	s_sub_i32 s12, 0x44, s11
	s_min_i32 s12, s12, 4
	s_abs_i32 s13, s12
	v_cvt_f32_u32_e32 v4, s13
	s_sub_i32 s23, 0, s13
	s_mul_i32 s10, s10, s6
	v_readlane_b32 s6, v254, 53
	v_rcp_iflag_f32_e32 v4, v4
	s_sub_i32 s6, s6, s10
	s_abs_i32 s22, s6
	s_xor_b32 s10, s6, s12
	v_mul_f32_e32 v4, 0x4f7ffffe, v4
	v_cvt_u32_f32_e32 v4, v4
	s_ashr_i32 s10, s10, 31
	v_lshlrev_b32_e32 v7, 5, v16
	v_ashrrev_i16_sdwa v2, v10, sext(v2) dst_sel:DWORD dst_unused:UNUSED_PAD src0_sel:DWORD src1_sel:BYTE_0
	v_readfirstlane_b32 s30, v4
	s_mul_i32 s23, s23, s30
	s_mul_hi_u32 s23, s30, s23
	s_add_i32 s30, s30, s23
	s_mul_hi_u32 s23, s22, s30
	s_mul_i32 s30, s23, s13
	s_sub_i32 s22, s22, s30
	s_add_i32 s30, s23, 1
	s_sub_i32 s38, s22, s13
	s_cmp_ge_u32 s22, s13
	s_cselect_b32 s23, s30, s23
	s_cselect_b32 s22, s38, s22
	s_add_i32 s30, s23, 1
	s_cmp_ge_u32 s22, s13
	s_cselect_b32 s13, s30, s23
	s_abs_i32 s7, s7
	v_cvt_f32_u32_e32 v4, s7
	s_xor_b32 s13, s13, s10
	s_sub_i32 s10, s13, s10
	s_mul_i32 s12, s10, s12
	v_rcp_iflag_f32_e32 v4, v4
	s_sub_i32 s6, s6, s12
	s_sub_i32 s12, 0, s7
	s_add_i32 s6, s6, s11
	v_mul_f32_e32 v4, 0x4f7ffffe, v4
	v_cvt_u32_f32_e32 v4, v4
	s_ashr_i32 s11, s10, 31
	s_abs_i32 s10, s10
	v_and_b32_e32 v7, 32, v7
	v_readfirstlane_b32 s13, v4
	s_mul_i32 s12, s12, s13
	s_mul_hi_u32 s12, s13, s12
	s_add_i32 s13, s13, s12
	s_mul_hi_u32 s12, s10, s13
	s_mul_i32 s12, s12, s7
	s_sub_i32 s10, s10, s12
	s_sub_i32 s12, s10, s7
	s_cmp_ge_u32 s10, s7
	s_cselect_b32 s10, s12, s10
	s_sub_i32 s12, s10, s7
	s_cmp_ge_u32 s10, s7
	s_cselect_b32 s7, s12, s10
	s_xor_b32 s7, s7, s11
	s_sub_i32 s10, s7, s11
	s_ashr_i32 s7, s6, 31
	s_ashr_i32 s11, s10, 31
	s_lshl_b64 s[12:13], s[6:7], 20
	s_lshl_b64 s[22:23], s[10:11], 20
	v_bfe_i32 v18, v2, 0, 16
	s_add_u32 s44, s19, s22
	v_add_lshl_u32 v7, v7, v18, 1
	s_addc_u32 s45, s20, s23
	s_add_i32 s7, s21, 0
	v_lshl_add_u32 v2, v6, 12, v7
	s_add_i32 m0, s7, 0x10000
	v_lshl_add_u32 v136, v5, 12, v7
	global_load_lds_dwordx4 v2, s[44:45]
	s_add_i32 m0, s7, 0x12000
	s_add_u32 s22, s44, 0x80000
	global_load_lds_dwordx4 v132, s[44:45]
	s_addc_u32 s23, s45, 0
	s_add_i32 m0, s7, 0x14000
	v_mov_b32_e32 v133, v3
	global_load_lds_dwordx4 v2, s[22:23]
	s_add_i32 m0, s7, 0x16000
	s_add_u32 s42, s9, s12
	s_addc_u32 s43, s18, s13
	s_add_i32 s11, s7, 0x2000
	global_load_lds_dwordx4 v132, s[22:23]
	s_mov_b32 m0, s7
	s_add_u32 s12, s42, 0x80000
	global_load_lds_dwordx4 v136, s[42:43]
	s_mov_b32 m0, s11
	s_addc_u32 s13, s43, 0
	s_add_i32 s30, s7, 0x4000
	global_load_lds_dwordx4 v134, s[42:43]
	s_mov_b32 m0, s30
	s_add_i32 s48, s7, 0x6000
	global_load_lds_dwordx4 v136, s[12:13]
	s_mov_b32 m0, s48
	v_mov_b32_e32 v137, v3
	global_load_lds_dwordx4 v134, s[12:13]
	v_mov_b32_e32 v135, v3
	v_lshl_add_u64 v[10:11], s[44:45], 0, v[2:3]
	v_lshl_add_u64 v[8:9], s[44:45], 0, v[132:133]
	v_lshl_add_u64 v[6:7], s[42:43], 0, v[136:137]
	s_cmp_lg_u32 s5, 1
	v_lshl_add_u64 v[4:5], s[42:43], 0, v[134:135]
	s_cbranch_scc1 .LBB0_506
	s_setprio 1
	s_barrier

; #define PG8_STAGE(bufoff, gbase, voff) do { _Pragma("unroll") for (int _i = 0; _i < 2; ++_i) \
;         __builtin_amdgcn_global_load_lds((const unsigned*)((const char*)(gbase) + (voff)[_i]), (PG8_LAS unsigned*)(lds + (bufoff) + ldsw + _i * 8192), 16, 0, 0); } while (0)
; #define PG8_BAR __builtin_amdgcn_s_barrier()
; template <class Epi, class Sched, bool ALIGN_EPI = true>
; __device__ __forceinline__ void gemm_phase(PG8_LAS unsigned char* lds, const Gemm g, const Sched& S, const Epi& E, const int tid) {
;     const int wid = __builtin_amdgcn_readfirstlane(tid >> 6), lane = tid & 63, wr = wid >> 2, wc = wid & 3, fr = lane & 15, fq = lane >> 4;
;     unsigned voffA[2], voffB[2];
; #pragma unroll
;     for (int i = 0; i < 2; ++i) { int R, C; stage_rc(tid * 16 + i * 8192, R, C); const int Rb = Epi::PERM ? ((R & ~31) + perm32(R & 31)) : R;
;         voffA[i] = (unsigned)(R * g.lda + C) * 2u; voffB[i] = (unsigned)(Rb * g.ldb + C) * 2u; }
;     const size_t kstep = (size_t)(BK * 2);
;     const size_t hstepA = (size_t)HALF * g.lda * 2, hstepB = (size_t)HALF * g.ldb * 2;
;     const size_t tstepA = 2 * hstepA, tstepB = 2 * hstepB;
;     const unsigned ldsw = (unsigned)wid * 1024u;
;     const int aoff = lds_byte(wr * 64 + fr, fq * 8), boff = lds_byte(wc * 32 + fr, fq * 8);
;     ...
;     Unit cur, nxt; int ui = 0;
;     if (!S.next(0, cur)) return;
;     f32x4 acc[2][2][4][2];
; #pragma unroll
;     for (int a = 0; a < 2; ++a)
; #pragma unroll
;         for (int b = 0; b < 2; ++b)
; #pragma unroll
;             for (int m = 0; m < 4; ++m)
; #pragma unroll
;                 for (int n = 0; n < 2; ++n) acc[a][b][m][n] = (f32x4){0.f, 0.f, 0.f, 0.f};
;     bf16x8 At[4][2], B0[2][2], B1[2][2];
;     const char* cA = (const char*)g.A + (size_t)cur.pm * tstepA + (size_t)cur.grp * g.gsA + (size_t)cur.kt0 * kstep; const char* cB = (const char*)g.Bt + (size_t)cur.pn * tstepB + (size_t)cur.grp * g.gsB + (size_t)cur.kt0 * kstep;
;     S.a_ready(cur);
;     PG8_STAGE(PG8_SB(0, 0), cB, voffB); PG8_STAGE(PG8_SB(0, 1), cB + hstepB, voffB); PG8_STAGE(PG8_SA(0, 0), cA, voffA); PG8_STAGE(PG8_SA(0, 1), cA + hstepA, voffA);
;     if (wr == 1) PG8_BAR;
.LBB0_1067:
	s_andn2_b64 vcc, exec, s[6:7]
	s_cbranch_vccnz .LBB0_1098
	v_ashrrev_i32_e32 v2, 31, v12
	v_lshrrev_b32_e32 v2, 26, v2
	v_add_u32_e32 v2, v12, v2
	v_ashrrev_i32_e32 v13, 6, v2
	v_bfe_i32 v2, v12, 27, 1
	v_lshlrev_b32_e32 v4, 4, v12
	v_lshrrev_b32_e32 v2, 22, v2
	v_add_u32_e32 v2, v4, v2
	v_and_b32_e32 v2, 0xfffffc00, v2
	v_sub_u32_e32 v2, v4, v2
	v_lshrrev_b32_e32 v5, 4, v2
	v_bitop3_b32 v2, v5, v2, 32 bitop3:0x6c
	v_ashrrev_i32_e32 v6, 31, v2
	v_lshrrev_b32_e32 v6, 26, v6
	s_waitcnt lgkmcnt(0)
	s_add_u32 s56, s38, 0x21e00000
	v_add_u32_e32 v6, v2, v6
	s_addc_u32 s57, s39, 0
	s_lshl_b32 s1, s86, 23
	v_lshlrev_b32_e32 v5, 3, v13
	v_ashrrev_i32_e32 v14, 6, v6
	v_and_b32_e32 v6, 0xc0, v6
	s_add_u32 s1, s38, s1
	v_and_b32_e32 v5, -16, v5
	v_sub_u32_e32 v2, v2, v6
	v_mov_b32_e32 v9, 1
	s_addc_u32 s6, s39, 0
	v_add_u32_e32 v5, v14, v5
	v_ashrrev_i16_sdwa v2, v9, sext(v2) dst_sel:DWORD dst_unused:UNUSED_PAD src0_sel:DWORD src1_sel:BYTE_0
	s_add_u32 s58, s1, 0x3400000
	v_lshlrev_b32_e32 v7, 5, v13
	v_bfe_i32 v15, v2, 0, 16
	v_lshlrev_b32_e32 v2, 1, v5
	v_lshrrev_b32_e32 v6, 2, v5
	v_and_b32_e32 v8, 3, v14
	s_mov_b32 s1, 0xfffe0
	v_and_b32_e32 v7, 32, v7
	v_and_b32_e32 v2, 24, v2
	v_and_b32_e32 v6, 4, v6
	v_and_or_b32 v8, v5, s1, v8
	v_or3_b32 v2, v8, v6, v2
	v_add_lshl_u32 v6, v7, v15, 1
	v_add_u32_e32 v4, 0x2000, v4
	v_lshl_add_u32 v210, v5, 12, v6
	v_ashrrev_i32_e32 v5, 31, v4
	v_lshrrev_b32_e32 v5, 22, v5
	v_add_u32_e32 v5, v4, v5
	v_ashrrev_i32_e32 v16, 10, v5
	v_mul_i32_i24_e32 v5, 0x400, v16
	v_sub_u32_e32 v4, v4, v5
	v_lshrrev_b32_e32 v5, 4, v4
	v_bitop3_b32 v4, v5, v4, 32 bitop3:0x6c
	v_lshl_add_u32 v2, v2, 12, v6
	v_ashrrev_i32_e32 v6, 31, v4
	v_lshrrev_b32_e32 v6, 26, v6
	v_lshlrev_b32_e32 v5, 3, v16
	v_add_u32_e32 v6, v4, v6
	v_and_b32_e32 v5, -16, v5
	v_ashrrev_i32_e32 v17, 6, v6
	v_add_u32_e32 v5, v17, v5
	v_and_b32_e32 v8, 3, v17
	s_addc_u32 s59, s6, 0
	v_and_or_b32 v8, v5, s1, v8
	s_ashr_i32 s20, s18, 6
	s_ashr_i32 s1, s0, 31
	s_ashr_i32 s19, s18, 8
	s_lshl_b32 s60, s20, 10
	s_lshl_b64 s[6:7], s[0:1], 20
	s_add_u32 s1, s56, s6
	s_addc_u32 s13, s57, s7
	s_ashr_i32 s11, s10, 31
	s_lshl_b64 s[6:7], s[10:11], 20
	v_and_b32_e32 v6, 0xc0, v6
	s_add_u32 s6, s58, s6
	v_sub_u32_e32 v4, v4, v6
	s_addc_u32 s7, s59, s7
	v_ashrrev_i16_sdwa v4, v9, sext(v4) dst_sel:DWORD dst_unused:UNUSED_PAD src0_sel:DWORD src1_sel:BYTE_0
	s_add_u32 s22, s6, s4
	v_lshlrev_b32_e32 v7, 5, v16
	v_bfe_i32 v18, v4, 0, 16
	v_lshlrev_b32_e32 v4, 1, v5
	v_lshrrev_b32_e32 v6, 2, v5
	s_addc_u32 s23, s7, s5
	s_add_i32 s11, s60, 0
	v_and_b32_e32 v7, 32, v7
	v_and_b32_e32 v4, 24, v4
	v_and_b32_e32 v6, 4, v6
	s_add_i32 m0, s11, 0x10000
	v_or3_b32 v4, v8, v6, v4
	v_add_lshl_u32 v6, v7, v18, 1
	global_load_lds_dwordx4 v2, s[22:23]
	s_add_i32 m0, s11, 0x12000
	v_lshl_add_u32 v214, v4, 12, v6
	s_add_u32 s6, s22, 0x80000
	global_load_lds_dwordx4 v214, s[22:23]
	s_addc_u32 s7, s23, 0
	s_add_i32 m0, s11, 0x14000
	v_lshl_add_u32 v212, v5, 12, v6
	global_load_lds_dwordx4 v2, s[6:7]
	s_add_i32 m0, s11, 0x16000
	s_add_u32 s12, s1, s4
	s_addc_u32 s13, s13, s5
	s_add_i32 s61, s11, 0x2000
	global_load_lds_dwordx4 v214, s[6:7]
	s_mov_b32 m0, s11
	s_add_u32 s4, s12, 0x80000
	global_load_lds_dwordx4 v210, s[12:13]
	s_mov_b32 m0, s61
	s_addc_u32 s5, s13, 0
	s_add_i32 s62, s11, 0x4000
	global_load_lds_dwordx4 v212, s[12:13]
	s_mov_b32 m0, s62
	s_add_i32 s63, s11, 0x6000
	global_load_lds_dwordx4 v210, s[4:5]
	s_mov_b32 m0, s63
	v_mov_b32_e32 v215, v3
	global_load_lds_dwordx4 v212, s[4:5]
	v_mov_b32_e32 v211, v3
	v_mov_b32_e32 v213, v3
	s_cmp_eq_u32 s19, 1
	v_lshl_add_u64 v[10:11], s[22:23], 0, v[2:3]
	v_lshl_add_u64 v[8:9], s[22:23], 0, v[214:215]
	v_lshl_add_u64 v[4:5], s[12:13], 0, v[210:211]
	s_cselect_b64 s[4:5], -1, 0
	s_cmp_lg_u32 s19, 1
	v_lshl_add_u64 v[6:7], s[12:13], 0, v[212:213]
	s_cbranch_scc1 .LBB0_1070
	s_setprio 1
	s_barrier

; #define PG8_STAGE(bufoff, gbase, voff) do { _Pragma("unroll") for (int _i = 0; _i < 2; ++_i) \
;         __builtin_amdgcn_global_load_lds((const unsigned*)((const char*)(gbase) + (voff)[_i]), (PG8_LAS unsigned*)(lds + (bufoff) + ldsw + _i * 8192), 16, 0, 0); } while (0)
; #define PG8_BAR __builtin_amdgcn_s_barrier()
; template <class Epi, class Sched, bool ALIGN_EPI = true>
; __device__ __forceinline__ void gemm_phase(PG8_LAS unsigned char* lds, const Gemm g, const Sched& S, const Epi& E, const int tid) {
;     const int wid = __builtin_amdgcn_readfirstlane(tid >> 6), lane = tid & 63, wr = wid >> 2, wc = wid & 3, fr = lane & 15, fq = lane >> 4;
;     unsigned voffA[2], voffB[2];
; #pragma unroll
;     for (int i = 0; i < 2; ++i) { int R, C; stage_rc(tid * 16 + i * 8192, R, C); const int Rb = Epi::PERM ? ((R & ~31) + perm32(R & 31)) : R;
;         voffA[i] = (unsigned)(R * g.lda + C) * 2u; voffB[i] = (unsigned)(Rb * g.ldb + C) * 2u; }
;     const size_t kstep = (size_t)(BK * 2);
;     const size_t hstepA = (size_t)HALF * g.lda * 2, hstepB = (size_t)HALF * g.ldb * 2;
;     const size_t tstepA = 2 * hstepA, tstepB = 2 * hstepB;
;     const unsigned ldsw = (unsigned)wid * 1024u;
;     const int aoff = lds_byte(wr * 64 + fr, fq * 8), boff = lds_byte(wc * 32 + fr, fq * 8);
;     ...
;     Unit cur, nxt; int ui = 0;
;     if (!S.next(0, cur)) return;
;     f32x4 acc[2][2][4][2];
; #pragma unroll
;     for (int a = 0; a < 2; ++a)
; #pragma unroll
;         for (int b = 0; b < 2; ++b)
; #pragma unroll
;             for (int m = 0; m < 4; ++m)
; #pragma unroll
;                 for (int n = 0; n < 2; ++n) acc[a][b][m][n] = (f32x4){0.f, 0.f, 0.f, 0.f};
;     bf16x8 At[4][2], B0[2][2], B1[2][2];
;     const char* cA = (const char*)g.A + (size_t)cur.pm * tstepA + (size_t)cur.grp * g.gsA + (size_t)cur.kt0 * kstep; const char* cB = (const char*)g.Bt + (size_t)cur.pn * tstepB + (size_t)cur.grp * g.gsB + (size_t)cur.kt0 * kstep;
;     S.a_ready(cur);
;     PG8_STAGE(PG8_SB(0, 0), cB, voffB); PG8_STAGE(PG8_SB(0, 1), cB + hstepB, voffB); PG8_STAGE(PG8_SA(0, 0), cA, voffA); PG8_STAGE(PG8_SA(0, 1), cA + hstepA, voffA);
;     if (wr == 1) PG8_BAR;
.LBB0_1229:
	s_andn2_b64 vcc, exec, s[12:13]
	s_cbranch_vccnz .LBB0_1269
	v_ashrrev_i32_e32 v2, 31, v12
	v_lshrrev_b32_e32 v2, 26, v2
	v_add_u32_e32 v2, v12, v2
	v_ashrrev_i32_e32 v13, 6, v2
	v_bfe_i32 v2, v12, 27, 1
	v_lshlrev_b32_e32 v4, 4, v12
	v_lshrrev_b32_e32 v2, 22, v2
	v_add_u32_e32 v2, v4, v2
	v_and_b32_e32 v2, 0xfffffc00, v2
	v_sub_u32_e32 v2, v4, v2
	v_lshrrev_b32_e32 v5, 4, v2
	v_bitop3_b32 v2, v5, v2, 32 bitop3:0x6c
	v_ashrrev_i32_e32 v6, 31, v2
	v_lshrrev_b32_e32 v6, 26, v6
	v_add_u32_e32 v6, v2, v6
	v_lshlrev_b32_e32 v5, 3, v13
	v_ashrrev_i32_e32 v14, 6, v6
	v_and_b32_e32 v6, 0xc0, v6
	v_and_b32_e32 v5, -16, v5
	v_sub_u32_e32 v2, v2, v6
	v_mov_b32_e32 v9, 1
	v_add_u32_e32 v5, v14, v5
	v_ashrrev_i16_sdwa v2, v9, sext(v2) dst_sel:DWORD dst_unused:UNUSED_PAD src0_sel:DWORD src1_sel:BYTE_0
	v_lshlrev_b32_e32 v7, 5, v13
	v_bfe_i32 v15, v2, 0, 16
	v_lshlrev_b32_e32 v2, 1, v5
	v_lshrrev_b32_e32 v6, 2, v5
	v_and_b32_e32 v8, 3, v14
	s_mov_b32 s3, 0xfffe0
	v_and_b32_e32 v7, 32, v7
	v_and_b32_e32 v2, 24, v2
	v_and_b32_e32 v6, 4, v6
	v_and_or_b32 v8, v5, s3, v8
	v_or3_b32 v2, v8, v6, v2
	v_add_lshl_u32 v6, v7, v15, 1
	v_add_u32_e32 v4, 0x2000, v4
	v_lshl_add_u32 v180, v5, 12, v6
	v_ashrrev_i32_e32 v5, 31, v4
	v_lshrrev_b32_e32 v5, 22, v5
	v_add_u32_e32 v5, v4, v5
	v_ashrrev_i32_e32 v16, 10, v5
	v_mul_i32_i24_e32 v5, 0x400, v16
	v_sub_u32_e32 v4, v4, v5
	v_readlane_b32 s12, v255, 22
	s_waitcnt lgkmcnt(0)
	s_add_u32 s81, s0, 0x1da00000
	v_lshrrev_b32_e32 v5, 4, v4
	s_mul_hi_u32 s11, s12, 0x2c00000
	s_mul_i32 s12, s12, 0x2c00000
	s_addc_u32 s82, s1, 0
	v_bitop3_b32 v4, v5, v4, 32 bitop3:0x6c
	s_add_u32 s12, s0, s12
	v_lshl_add_u32 v2, v2, 12, v6
	v_ashrrev_i32_e32 v6, 31, v4
	s_addc_u32 s11, s1, s11
	v_lshrrev_b32_e32 v6, 26, v6
	v_readlane_b32 s13, v255, 23
	s_add_u32 s83, s12, 0x4800000
	v_add_u32_e32 v6, v4, v6
	s_addc_u32 s84, s11, 0
	s_ashr_i32 s13, s8, 6
	v_lshlrev_b32_e32 v5, 3, v16
	v_ashrrev_i32_e32 v17, 6, v6
	v_and_b32_e32 v6, 0xc0, v6
	s_ashr_i32 s11, s10, 31
	s_ashr_i32 s73, s72, 31
	v_and_b32_e32 v5, -16, v5
	v_sub_u32_e32 v4, v4, v6
	s_ashr_i32 s12, s8, 8
	s_lshl_b32 s85, s13, 10
	s_lshl_b64 s[18:19], s[10:11], 20
	s_lshl_b64 s[20:21], s[72:73], 20
	v_add_u32_e32 v5, v17, v5
	v_ashrrev_i16_sdwa v4, v9, sext(v4) dst_sel:DWORD dst_unused:UNUSED_PAD src0_sel:DWORD src1_sel:BYTE_0
	s_add_u32 s76, s83, s20
	v_lshlrev_b32_e32 v7, 5, v16
	v_bfe_i32 v18, v4, 0, 16
	v_lshlrev_b32_e32 v4, 1, v5
	v_lshrrev_b32_e32 v6, 2, v5
	v_and_b32_e32 v8, 3, v17
	s_addc_u32 s77, s84, s21
	s_add_i32 s86, s85, 0
	v_and_b32_e32 v7, 32, v7
	v_and_b32_e32 v4, 24, v4
	v_and_b32_e32 v6, 4, v6
	v_and_or_b32 v8, v5, s3, v8
	s_add_i32 m0, s86, 0x10000
	v_or3_b32 v4, v8, v6, v4
	v_add_lshl_u32 v6, v7, v18, 1
	global_load_lds_dwordx4 v2, s[76:77]
	s_add_i32 m0, s86, 0x12000
	v_lshl_add_u32 v184, v4, 12, v6
	s_add_u32 s20, s76, 0x80000
	global_load_lds_dwordx4 v184, s[76:77]
	s_addc_u32 s21, s77, 0
	s_add_i32 m0, s86, 0x14000
	v_lshl_add_u32 v182, v5, 12, v6
	global_load_lds_dwordx4 v2, s[20:21]
	s_add_i32 m0, s86, 0x16000
	s_add_u32 s74, s81, s18
	s_addc_u32 s75, s82, s19
	s_add_i32 s87, s86, 0x2000
	global_load_lds_dwordx4 v184, s[20:21]
	s_mov_b32 m0, s86
	s_add_u32 s18, s74, 0x80000
	global_load_lds_dwordx4 v180, s[74:75]
	s_mov_b32 m0, s87
	s_addc_u32 s19, s75, 0
	s_add_i32 s88, s86, 0x4000
	global_load_lds_dwordx4 v182, s[74:75]
	s_mov_b32 m0, s88
	s_add_i32 s89, s86, 0x6000
	global_load_lds_dwordx4 v180, s[18:19]
	s_mov_b32 m0, s89
	v_mov_b32_e32 v185, v3
	global_load_lds_dwordx4 v182, s[18:19]
	v_mov_b32_e32 v181, v3
	v_mov_b32_e32 v183, v3
	s_cmp_eq_u32 s12, 1
	v_lshl_add_u64 v[10:11], s[76:77], 0, v[2:3]
	v_lshl_add_u64 v[8:9], s[76:77], 0, v[184:185]
	v_lshl_add_u64 v[4:5], s[74:75], 0, v[180:181]
	s_cselect_b64 s[52:53], -1, 0
	s_cmp_lg_u32 s12, 1
	v_lshl_add_u64 v[6:7], s[74:75], 0, v[182:183]
	s_cbranch_scc1 .LBB0_1232
	s_setprio 1
	s_barrier

; #define PG8_STAGE(bufoff, gbase, voff) do { _Pragma("unroll") for (int _i = 0; _i < 2; ++_i) \
;         __builtin_amdgcn_global_load_lds((const unsigned*)((const char*)(gbase) + (voff)[_i]), (PG8_LAS unsigned*)(lds + (bufoff) + ldsw + _i * 8192), 16, 0, 0); } while (0)
; #define PG8_BAR __builtin_amdgcn_s_barrier()
; template <class Epi, class Sched, bool ALIGN_EPI = true>
; __device__ __forceinline__ void gemm_phase(PG8_LAS unsigned char* lds, const Gemm g, const Sched& S, const Epi& E, const int tid) {
;     const int wid = __builtin_amdgcn_readfirstlane(tid >> 6), lane = tid & 63, wr = wid >> 2, wc = wid & 3, fr = lane & 15, fq = lane >> 4;
;     unsigned voffA[2], voffB[2];
; #pragma unroll
;     for (int i = 0; i < 2; ++i) { int R, C; stage_rc(tid * 16 + i * 8192, R, C); const int Rb = Epi::PERM ? ((R & ~31) + perm32(R & 31)) : R;
;         voffA[i] = (unsigned)(R * g.lda + C) * 2u; voffB[i] = (unsigned)(Rb * g.ldb + C) * 2u; }
;     const size_t kstep = (size_t)(BK * 2);
;     const size_t hstepA = (size_t)HALF * g.lda * 2, hstepB = (size_t)HALF * g.ldb * 2;
;     const size_t tstepA = 2 * hstepA, tstepB = 2 * hstepB;
;     const unsigned ldsw = (unsigned)wid * 1024u;
;     const int aoff = lds_byte(wr * 64 + fr, fq * 8), boff = lds_byte(wc * 32 + fr, fq * 8);
;     ...
;     Unit cur, nxt; int ui = 0;
;     if (!S.next(0, cur)) return;
;     f32x4 acc[2][2][4][2];
; #pragma unroll
;     for (int a = 0; a < 2; ++a)
; #pragma unroll
;         for (int b = 0; b < 2; ++b)
; #pragma unroll
;             for (int m = 0; m < 4; ++m)
; #pragma unroll
;                 for (int n = 0; n < 2; ++n) acc[a][b][m][n] = (f32x4){0.f, 0.f, 0.f, 0.f};
;     bf16x8 At[4][2], B0[2][2], B1[2][2];
;     const char* cA = (const char*)g.A + (size_t)cur.pm * tstepA + (size_t)cur.grp * g.gsA + (size_t)cur.kt0 * kstep; const char* cB = (const char*)g.Bt + (size_t)cur.pn * tstepB + (size_t)cur.grp * g.gsB + (size_t)cur.kt0 * kstep;
;     S.a_ready(cur);
;     PG8_STAGE(PG8_SB(0, 0), cB, voffB); PG8_STAGE(PG8_SB(0, 1), cB + hstepB, voffB); PG8_STAGE(PG8_SA(0, 0), cA, voffA); PG8_STAGE(PG8_SA(0, 1), cA + hstepA, voffA);
;     if (wr == 1) PG8_BAR;
.LBB0_1394:
	s_andn2_b64 vcc, exec, s[0:1]
	s_cbranch_vccnz .LBB0_1425
	v_ashrrev_i32_e32 v2, 31, v12
	v_lshrrev_b32_e32 v2, 26, v2
	v_add_u32_e32 v2, v12, v2
	v_ashrrev_i32_e32 v13, 6, v2
	v_bfe_i32 v2, v12, 27, 1
	v_lshlrev_b32_e32 v4, 4, v12
	v_lshrrev_b32_e32 v2, 22, v2
	v_add_u32_e32 v2, v4, v2
	v_and_b32_e32 v2, 0xfffffc00, v2
	v_sub_u32_e32 v2, v4, v2
	v_lshrrev_b32_e32 v5, 4, v2
	v_readlane_b32 s0, v255, 22
	v_bitop3_b32 v2, v5, v2, 32 bitop3:0x6c
	v_readlane_b32 s1, v255, 23
	s_mov_b32 s6, s0
	s_waitcnt lgkmcnt(0)
	s_add_u32 s18, s10, 0x3d800000
	v_ashrrev_i32_e32 v6, 31, v2
	s_mul_i32 s1, s6, 0x1680000
	s_addc_u32 s19, s11, 0
	v_lshrrev_b32_e32 v6, 26, v6
	s_mul_hi_u32 s0, s0, 0x1680000
	s_add_u32 s1, s10, s1
	v_lshlrev_b32_e32 v5, 3, v13
	v_add_u32_e32 v6, v2, v6
	s_addc_u32 s0, s11, s0
	v_and_b32_e32 v5, -16, v5
	v_ashrrev_i32_e32 v15, 6, v6
	v_and_b32_e32 v6, 0xc0, v6
	s_add_u32 s30, s1, 0xf800000
	v_add_u32_e32 v5, v15, v5
	v_lshlrev_b32_e32 v7, 5, v13
	v_sub_u32_e32 v2, v2, v6
	v_mov_b32_e32 v9, 1
	s_addc_u32 s50, s0, 0
	v_and_b32_e32 v14, 32, v7
	v_ashrrev_i16_sdwa v2, v9, sext(v2) dst_sel:DWORD dst_unused:UNUSED_PAD src0_sel:DWORD src1_sel:BYTE_0
	v_lshlrev_b32_e32 v6, 1, v5
	v_lshrrev_b32_e32 v7, 2, v5
	v_and_b32_e32 v8, 3, v15
	s_mov_b32 s0, 0x1ffffe0
	v_bfe_i32 v16, v2, 0, 16
	v_and_b32_e32 v6, 24, v6
	v_and_b32_e32 v7, 4, v7
	v_and_or_b32 v8, v5, s0, v8
	s_movk_i32 s1, 0x1680
	v_add_u32_e32 v2, v14, v16
	v_or3_b32 v6, v8, v7, v6
	v_mul_lo_u32 v5, v5, s1
	v_add_lshl_u32 v210, v2, v5, 1
	v_mul_lo_u32 v5, v6, s1
	v_add_u32_e32 v4, 0x2000, v4
	v_add_lshl_u32 v2, v5, v2, 1
	v_ashrrev_i32_e32 v5, 31, v4
	v_lshrrev_b32_e32 v5, 22, v5
	v_add_u32_e32 v5, v4, v5
	v_ashrrev_i32_e32 v17, 10, v5
	v_mul_i32_i24_e32 v5, 0x400, v17
	v_sub_u32_e32 v4, v4, v5
	v_lshrrev_b32_e32 v5, 4, v4
	v_bitop3_b32 v4, v5, v4, 32 bitop3:0x6c
	v_ashrrev_i32_e32 v6, 31, v4
	v_lshrrev_b32_e32 v6, 26, v6
	v_lshlrev_b32_e32 v5, 3, v17
	v_add_u32_e32 v6, v4, v6
	v_and_b32_e32 v5, -16, v5
	v_ashrrev_i32_e32 v19, 6, v6
	v_and_b32_e32 v6, 0xc0, v6
	v_add_u32_e32 v5, v19, v5
	v_lshlrev_b32_e32 v7, 5, v17
	v_sub_u32_e32 v4, v4, v6
	v_and_b32_e32 v18, 32, v7
	v_ashrrev_i16_sdwa v4, v9, sext(v4) dst_sel:DWORD dst_unused:UNUSED_PAD src0_sel:DWORD src1_sel:BYTE_0
	v_lshlrev_b32_e32 v6, 1, v5
	v_lshrrev_b32_e32 v7, 2, v5
	v_and_b32_e32 v8, 3, v19
	v_bfe_i32 v20, v4, 0, 16
	v_and_b32_e32 v6, 24, v6
	v_and_b32_e32 v7, 4, v7
	v_and_or_b32 v8, v5, s0, v8
	v_add_u32_e32 v4, v18, v20
	v_or3_b32 v6, v8, v7, v6
	v_mul_lo_u32 v5, v5, s1
	s_ashr_i32 s38, s22, 6
	s_ashr_i32 s23, s22, 8
	v_add_lshl_u32 v212, v4, v5, 1
	v_mul_lo_u32 v5, v6, s1
	s_lshl_b32 s51, s38, 10
	s_mul_i32 s1, s65, 0x2d0000
	s_mul_hi_i32 s0, s65, 0x2d0000
	s_add_u32 s6, s18, s1
	s_addc_u32 s7, s19, s0
	s_mul_i32 s1, s66, 0x2d0000
	s_mul_hi_i32 s0, s66, 0x2d0000
	s_add_u32 s1, s30, s1
	s_addc_u32 s0, s50, s0
	s_add_u32 s12, s1, s4
	s_addc_u32 s13, s0, s5
	s_add_i32 s52, s51, 0
	s_add_i32 m0, s52, 0x10000
	v_add_lshl_u32 v214, v5, v4, 1
	global_load_lds_dwordx4 v2, s[12:13]
	s_add_i32 m0, s52, 0x12000
	s_add_u32 s0, s12, 0x168000
	global_load_lds_dwordx4 v214, s[12:13]
	s_addc_u32 s1, s13, 0
	s_add_i32 m0, s52, 0x14000
	v_mov_b32_e32 v215, v3
	global_load_lds_dwordx4 v2, s[0:1]
	s_add_i32 m0, s52, 0x16000
	v_mov_b32_e32 v211, v3
	global_load_lds_dwordx4 v214, s[0:1]
	s_add_u32 s0, s6, s4
	s_addc_u32 s1, s7, s5
	s_add_i32 s53, s52, 0x2000
	s_mov_b32 m0, s52
	s_add_u32 s4, s0, 0x168000
	global_load_lds_dwordx4 v210, s[0:1]
	s_mov_b32 m0, s53
	s_addc_u32 s5, s1, 0
	s_add_i32 s54, s52, 0x4000
	global_load_lds_dwordx4 v212, s[0:1]
	s_mov_b32 m0, s54
	s_add_i32 s55, s52, 0x6000
	global_load_lds_dwordx4 v210, s[4:5]
	s_mov_b32 m0, s55
	v_mov_b32_e32 v213, v3
	global_load_lds_dwordx4 v212, s[4:5]
	s_cmp_eq_u32 s23, 1
	v_lshl_add_u64 v[10:11], s[12:13], 0, v[2:3]
	v_lshl_add_u64 v[8:9], s[12:13], 0, v[214:215]
	v_lshl_add_u64 v[4:5], s[0:1], 0, v[210:211]
	s_cselect_b64 s[4:5], -1, 0
	s_cmp_lg_u32 s23, 1
	v_lshl_add_u64 v[6:7], s[0:1], 0, v[212:213]
	s_cbranch_scc1 .LBB0_1397
	s_setprio 1
	s_barrier
